# mixer queue: first unit of every workgroup assigned statically from its rank on the XCD (no head/list atomics on the critical path at mixer start); later list claims offset by 30
# baseline (speedup 1.0000x reference)
.LBB0_848:
	s_or_b64 exec, exec, s[0:1]
	s_lshl_b32 s96, s74, 6
	s_lshl_b64 s[0:1], s[96:97], 2
	s_add_u32 s70, s40, s0
	s_addc_u32 s71, s41, s1
	s_lshl_b32 s96, s74, 9
	s_lshl_b64 s[0:1], s[96:97], 2
	v_readlane_b32 s4, v254, 29
	s_add_u32 s82, s4, s0
	v_readlane_b32 s0, v254, 30
	s_addc_u32 s83, s0, s1
	v_mov_b32_e32 v197, 0x7d0
	s_mov_b64 s[84:85], 0
	v_mov_b32_e32 v196, 0
	s_waitcnt lgkmcnt(0)
	s_barrier
	s_and_saveexec_b64 s[0:1], s[26:27]
	s_cbranch_execz .LBB0_900
	s_mov_b64 s[6:7], exec
	v_mbcnt_lo_u32_b32 v0, s6, 0
	v_mbcnt_hi_u32_b32 v0, s7, v0
	v_cmp_eq_u32_e32 vcc, 0, v0
	s_and_saveexec_b64 s[4:5], vcc
	s_cbranch_execz .LBB0_851
	s_bcnt1_i32_b64 s6, s[6:7]
	v_mov_b32_e32 v1, s6
	v_readlane_b32 s6, v255, 46
	s_and_b32 s7, s3, 7
	s_lshl_b32 s7, s7, 2
	s_cmp_lg_u32 s6, 0
	s_cselect_b32 s6, s7, 0
	v_mov_b32_e32 v2, s6
	v_readlane_b32 s6, v255, 46
	s_cmp_lg_u32 s6, 0
	s_cbranch_scc1 .LBB0_851
	global_atomic_add v1, v2, v1, s[70:71] offset:256 sc0
.LBB0_851:
	s_or_b64 exec, exec, s[4:5]
	s_waitcnt vmcnt(0)
	v_readfirstlane_b32 s4, v1
	v_mov_b32_e32 v196, 0
	s_nop 0
	v_add_u32_e32 v197, s4, v0
	v_readlane_b32 s4, v255, 46
	s_lshr_b32 s5, s2, 3
	s_cmp_lg_u32 s4, 0
	s_cbranch_scc0 .Lmy_fc_glob
	v_mov_b32_e32 v197, s5
.Lmy_fc_glob:
	v_readlane_b32 s4, v255, 46
	s_and_b32 s5, s3, 7
	s_lshl_b32 s5, s5, 1
	s_cmp_lg_u32 s4, 0
	s_cselect_b32 s5, s5, 0
	s_cselect_b32 s4, 2, 16
	v_cmp_gt_u32_e32 vcc, s4, v197
	v_add_u32_e32 v2, s5, v197
	v_mov_b32_e32 v4, 16
	s_nop 0
	v_cndmask_b32_e32 v197, v4, v2, vcc
	v_cmp_lt_i32_e32 vcc, 15, v197
	s_mov_b64 s[4:5], 0
	s_and_saveexec_b64 s[6:7], vcc
	s_cbranch_execz .LBB0_899
	v_mov_b32_e32 v196, 0
	s_mov_b64 s[8:9], 0
	s_branch .LBB0_855

.LBB0_855:
	v_add_u32_e32 v0, s3, v196
	v_and_b32_e32 v1, 7, v0
	v_lshlrev_b32_e32 v0, 8, v1
	v_readlane_b32 s58, v255, 46
	s_cmp_lg_u32 s58, 0
	s_cbranch_scc0 .Lmy_fc_atom
	s_lshr_b32 s58, s2, 3
	s_sub_i32 s58, s58, 2
	v_mov_b32_e32 v0, s58
	s_branch .Lmy_fc_have
.Lmy_fc_atom:
	global_atomic_add v0, v0, v230, s[82:83] sc0
	s_waitcnt vmcnt(0)
.Lmy_fc_have:
	v_add_u32_e32 v2, 0xfffffff0, v0
	v_add_u32_e32 v4, 0xfffffff0, v0
	v_cmp_gt_u32_e32 vcc, 0xe8, v0
	s_nop 1
	v_cndmask_b32_e32 v2, v2, v4, vcc
	v_add_u32_e32 v4, 0x30, v0
	v_cmp_gt_u32_e32 vcc, 0xc8, v0
	s_nop 1
	v_cndmask_b32_e32 v2, v2, v4, vcc
	v_add_u32_e32 v4, 0xfffffff8, v0
	v_cmp_gt_u32_e32 vcc, 0xb8, v0
	s_nop 1
	v_cndmask_b32_e32 v2, v2, v4, vcc
	v_add_u32_e32 v4, 0xfffffff8, v0
	v_cmp_gt_u32_e32 vcc, 0xa8, v0
	s_nop 1
	v_cndmask_b32_e32 v2, v2, v4, vcc
	v_add_u32_e32 v4, 0xfffffff8, v0
	v_cmp_gt_u32_e32 vcc, 0x98, v0
	s_nop 1
	v_cndmask_b32_e32 v2, v2, v4, vcc
	v_add_u32_e32 v4, 0xffffffb8, v0
	v_cmp_gt_u32_e32 vcc, 0x78, v0
	s_nop 1
	v_cndmask_b32_e32 v2, v2, v4, vcc
	v_add_u32_e32 v4, 0xffffffb8, v0
	v_cmp_gt_u32_e32 vcc, 0x68, v0
	s_nop 1
	v_cndmask_b32_e32 v2, v2, v4, vcc
	v_add_u32_e32 v4, 0x28, v0
	v_cmp_gt_u32_e32 vcc, 0x48, v0
	s_nop 1
	v_cndmask_b32_e32 v2, v2, v4, vcc
	v_add_u32_e32 v4, 0x28, v0
	v_cmp_gt_u32_e32 vcc, 0x28, v0
	s_nop 1
	v_cndmask_b32_e32 v2, v2, v4, vcc
	v_add_u32_e32 v4, 0xb0, v0
	v_cmp_gt_u32_e32 vcc, 0x8, v0
	s_nop 1
	v_cndmask_b32_e32 v2, v2, v4, vcc
	v_cmp_gt_u32_e32 vcc, 0xf8, v0
	s_nop 1
	v_cndmask_b32_e32 v0, v0, v2, vcc
	s_nop 1
	v_cmp_lt_i32_e32 vcc, s95, v0
	s_and_saveexec_b64 s[4:5], vcc
	s_xor_b64 s[4:5], exec, s[4:5]
	v_add_u32_e32 v196, 1, v196
	s_or_saveexec_b64 s[4:5], s[4:5]
	v_mov_b32_e32 v197, 0x7d0
	s_xor_b64 exec, exec, s[4:5]
	s_cbranch_execz .LBB0_854
	v_cmp_lt_i32_e32 vcc, 31, v0
	s_and_saveexec_b64 s[10:11], vcc
	s_xor_b64 s[10:11], exec, s[10:11]
	s_cbranch_execz .LBB0_896
	v_cmp_lt_u32_e32 vcc, 47, v0
	s_and_saveexec_b64 s[12:13], vcc
	s_xor_b64 s[12:13], exec, s[12:13]
	s_cbranch_execz .LBB0_893
	s_movk_i32 s14, 0x4f
	v_cmp_lt_u32_e32 vcc, s14, v0
	s_and_saveexec_b64 s[14:15], vcc
	s_xor_b64 s[14:15], exec, s[14:15]
	s_cbranch_execz .LBB0_890
	s_movk_i32 s16, 0x6f
	v_cmp_lt_u32_e32 vcc, s16, v0
	s_and_saveexec_b64 s[16:17], vcc
	s_xor_b64 s[16:17], exec, s[16:17]
	s_cbranch_execz .LBB0_887
	s_movk_i32 s18, 0x8f
	v_cmp_lt_u32_e32 vcc, s18, v0
	s_and_saveexec_b64 s[18:19], vcc
	s_xor_b64 s[18:19], exec, s[18:19]
	s_cbranch_execz .LBB0_884
	s_movk_i32 s20, 0x9f
	v_cmp_lt_u32_e32 vcc, s20, v0
	s_and_saveexec_b64 s[20:21], vcc
	s_xor_b64 s[20:21], exec, s[20:21]
	s_cbranch_execz .LBB0_881
	s_movk_i32 s22, 0xaf
	v_cmp_lt_u32_e32 vcc, s22, v0
	s_and_saveexec_b64 s[22:23], vcc
	s_xor_b64 s[22:23], exec, s[22:23]
	s_cbranch_execz .LBB0_878
	s_movk_i32 s24, 0xb7
	v_cmp_lt_u32_e32 vcc, s24, v0
	s_and_saveexec_b64 s[24:25], vcc
	s_xor_b64 s[24:25], exec, s[24:25]
	s_cbranch_execz .LBB0_875
	s_movk_i32 s33, 0xd7
	v_cmp_lt_u32_e32 vcc, s33, v0
	s_and_saveexec_b64 s[34:35], vcc
	s_xor_b64 s[34:35], exec, s[34:35]
	s_cbranch_execz .LBB0_872
	s_movk_i32 s33, 0xe7
	v_cmp_lt_u32_e32 vcc, s33, v0
	v_lshlrev_b32_e32 v1, 4, v1
	s_and_saveexec_b64 s[44:45], vcc
	s_xor_b64 s[56:57], exec, s[44:45]
	s_movk_i32 s33, 0x668
	v_add3_u32 v197, v0, v1, s33
	s_andn2_saveexec_b64 s[56:57], s[56:57]
	s_movk_i32 s33, 0x5f8
	v_add3_u32 v197, v0, v1, s33
	s_or_b64 exec, exec, s[56:57]

.LBB0_899:
	s_or_b64 exec, exec, s[6:7]
	s_and_b64 s[84:85], s[4:5], exec
	v_readlane_b32 s4, v255, 46
	s_cmp_lg_u32 s4, 0
	s_cselect_b64 s[84:85], exec, s[84:85]

.LBB0_915:
	v_add_u32_e32 v0, s3, v196
	v_and_b32_e32 v1, 7, v0
	v_lshlrev_b32_e32 v0, 8, v1
	global_atomic_add v0, v0, v230, s[82:83] sc0
	s_waitcnt vmcnt(0)
	v_readlane_b32 s58, v255, 46
	s_cmp_lg_u32 s58, 0
	s_cselect_b32 s58, 30, 0
	s_nop 0
	v_add_u32_e32 v0, s58, v0
	v_add_u32_e32 v2, 0xfffffff0, v0
	v_add_u32_e32 v4, 0xfffffff0, v0
	v_cmp_gt_u32_e32 vcc, 0xe8, v0
	s_nop 1
	v_cndmask_b32_e32 v2, v2, v4, vcc
	v_add_u32_e32 v4, 0x30, v0
	v_cmp_gt_u32_e32 vcc, 0xc8, v0
	s_nop 1
	v_cndmask_b32_e32 v2, v2, v4, vcc
	v_add_u32_e32 v4, 0xfffffff8, v0
	v_cmp_gt_u32_e32 vcc, 0xb8, v0
	s_nop 1
	v_cndmask_b32_e32 v2, v2, v4, vcc
	v_add_u32_e32 v4, 0xfffffff8, v0
	v_cmp_gt_u32_e32 vcc, 0xa8, v0
	s_nop 1
	v_cndmask_b32_e32 v2, v2, v4, vcc
	v_add_u32_e32 v4, 0xfffffff8, v0
	v_cmp_gt_u32_e32 vcc, 0x98, v0
	s_nop 1
	v_cndmask_b32_e32 v2, v2, v4, vcc
	v_add_u32_e32 v4, 0xffffffb8, v0
	v_cmp_gt_u32_e32 vcc, 0x78, v0
	s_nop 1
	v_cndmask_b32_e32 v2, v2, v4, vcc
	v_add_u32_e32 v4, 0xffffffb8, v0
	v_cmp_gt_u32_e32 vcc, 0x68, v0
	s_nop 1
	v_cndmask_b32_e32 v2, v2, v4, vcc
	v_add_u32_e32 v4, 0x28, v0
	v_cmp_gt_u32_e32 vcc, 0x48, v0
	s_nop 1
	v_cndmask_b32_e32 v2, v2, v4, vcc
	v_add_u32_e32 v4, 0x28, v0
	v_cmp_gt_u32_e32 vcc, 0x28, v0
	s_nop 1
	v_cndmask_b32_e32 v2, v2, v4, vcc
	v_add_u32_e32 v4, 0xb0, v0
	v_cmp_gt_u32_e32 vcc, 0x8, v0
	s_nop 1
	v_cndmask_b32_e32 v2, v2, v4, vcc
	v_cmp_gt_u32_e32 vcc, 0xf8, v0
	s_nop 1
	v_cndmask_b32_e32 v0, v0, v2, vcc
	s_nop 1
	v_cmp_lt_i32_e32 vcc, s95, v0
	s_and_saveexec_b64 s[6:7], vcc
	s_xor_b64 s[6:7], exec, s[6:7]
	v_add_u32_e32 v196, 1, v196
	s_or_saveexec_b64 s[6:7], s[6:7]
	v_mov_b32_e32 v197, 0x7d0
	s_xor_b64 exec, exec, s[6:7]
	s_cbranch_execz .LBB0_914
	v_cmp_lt_i32_e32 vcc, 31, v0
	s_and_saveexec_b64 s[14:15], vcc
	s_xor_b64 s[14:15], exec, s[14:15]
	s_cbranch_execz .LBB0_956
	v_cmp_lt_u32_e32 vcc, 47, v0
	s_and_saveexec_b64 s[16:17], vcc
	s_xor_b64 s[16:17], exec, s[16:17]
	s_cbranch_execz .LBB0_953
	s_movk_i32 s18, 0x4f
	v_cmp_lt_u32_e32 vcc, s18, v0
	s_and_saveexec_b64 s[18:19], vcc
	s_xor_b64 s[18:19], exec, s[18:19]
	s_cbranch_execz .LBB0_950
	s_movk_i32 s20, 0x6f
	v_cmp_lt_u32_e32 vcc, s20, v0
	s_and_saveexec_b64 s[20:21], vcc
	s_xor_b64 s[20:21], exec, s[20:21]
	s_cbranch_execz .LBB0_947
	s_movk_i32 s22, 0x8f
	v_cmp_lt_u32_e32 vcc, s22, v0
	s_and_saveexec_b64 s[22:23], vcc
	s_xor_b64 s[22:23], exec, s[22:23]
	s_cbranch_execz .LBB0_944
	s_movk_i32 s24, 0x9f
	v_cmp_lt_u32_e32 vcc, s24, v0
	s_and_saveexec_b64 s[24:25], vcc
	s_xor_b64 s[24:25], exec, s[24:25]
	s_cbranch_execz .LBB0_941
	s_movk_i32 s33, 0xaf
	v_cmp_lt_u32_e32 vcc, s33, v0
	s_and_saveexec_b64 s[34:35], vcc
	s_xor_b64 s[34:35], exec, s[34:35]
	s_cbranch_execz .LBB0_938
	s_movk_i32 s33, 0xb7
	v_cmp_lt_u32_e32 vcc, s33, v0
	s_and_saveexec_b64 s[44:45], vcc
	s_xor_b64 s[56:57], exec, s[44:45]
	s_cbranch_execz .LBB0_935
	s_movk_i32 s33, 0xd7
	v_cmp_lt_u32_e32 vcc, s33, v0
	s_and_saveexec_b64 s[44:45], vcc
	s_xor_b64 s[76:77], exec, s[44:45]
	s_cbranch_execz .LBB0_932
	s_movk_i32 s33, 0xe7
	v_cmp_lt_u32_e32 vcc, s33, v0
	v_lshlrev_b32_e32 v1, 4, v1
	s_and_saveexec_b64 s[44:45], vcc
	s_xor_b64 s[66:67], exec, s[44:45]
	s_movk_i32 s33, 0x668
	v_add3_u32 v197, v0, v1, s33
	s_andn2_saveexec_b64 s[66:67], s[66:67]
	s_movk_i32 s33, 0x5f8
	v_add3_u32 v197, v0, v1, s33
	s_or_b64 exec, exec, s[66:67]
